# v15: v6 + both helper kinds prefetch the GDN scan's operands (rows on one, KT/VT/TM/ATT tiles on the other; GDN is the scan phase's critical path, HGRN has slack), prefetch lead 2 chunks
# speedup vs baseline: 1.0314x; 1.0046x over previous
.LBB0_303:
	v_readlane_b32 s4, v253, 41
	v_readlane_b32 s12, v253, 49
	v_readlane_b32 s13, v253, 50
	v_readlane_b32 s14, v253, 51
	v_readlane_b32 s15, v253, 52
	v_readlane_b32 s16, v253, 53
	v_readlane_b32 s17, v253, 54
	v_readlane_b32 s18, v253, 55
	v_readlane_b32 s19, v253, 56
	s_mov_b64 s[12:13], s[16:17]
	v_readlane_b32 s8, v253, 45
	s_mov_b64 s[14:15], s[18:19]
	v_readlane_b32 s9, v253, 46
	s_add_u32 s8, s14, 0x1f000000
	s_addc_u32 s9, s15, 0
	s_cmpk_lt_i32 s64, 0xc0
	v_readlane_b32 s5, v253, 42
	v_readlane_b32 s6, v253, 43
	v_readlane_b32 s7, v253, 44
	v_readlane_b32 s10, v253, 47
	v_readlane_b32 s11, v253, 48
	s_cbranch_scc1 .LBB0_323
	s_lshl_b32 s2, s64, 2
	s_add_i32 s6, s64, 0xffffff40
	s_and_b32 s3, s2, 28
	s_bfe_u32 s4, s64, 0x20003
	s_or_b32 s7, s3, s4
	s_bfe_u32 s12, s2, 0x20003
	s_mov_b32 s2, 0
	v_readlane_b32 s36, v253, 41
	s_or_b32 s2, s7, s2
	v_readlane_b32 s48, v253, 53
	v_readlane_b32 s49, v253, 54
	s_lshl_b32 s2, s2, 6
	s_mov_b32 s3, 0
	v_readlane_b32 s50, v253, 55
	v_readlane_b32 s51, v253, 56
	s_mov_b64 s[16:17], s[48:49]
	s_and_b32 s10, s7, 7
	s_lshl_b64 s[4:5], s[2:3], 2
	s_mov_b64 s[18:19], s[50:51]
	s_add_u32 s2, s18, s4
	s_addc_u32 s5, s19, s5
	s_add_u32 s4, s2, 0x8000
	s_addc_u32 s5, s5, 0
	s_lshl_b32 s2, s12, 9
	s_lshl_b32 s20, s7, 6
	s_or_b32 s21, s2, s10
	s_waitcnt vmcnt(0)
	v_lshlrev_b32_e32 v6, 3, v0
	v_mov_b32_e32 v3, 0
	v_lshlrev_b32_e32 v2, 6, v0
	v_and_b32_e32 v1, 0x78, v6
	s_cmp_gt_u32 s6, 31
	v_and_b32_e32 v2, 0x7c00, v2
	v_mov_b32_e32 v4, v3
	v_mov_b32_e32 v5, v3
	v_lshl_or_b32 v1, s10, 7, v1
	s_cselect_b64 s[6:7], -1, 0
	s_not_b64 s[98:99], s[6:7]
	s_add_u32 s10, s18, 0x17000000
	v_lshl_or_b32 v14, s12, 22, v2
	v_mov_b32_e32 v2, v3
	v_lshlrev_b32_e32 v12, 1, v6
	v_mov_b64_e32 v[6:7], v[4:5]
	s_addc_u32 s11, s19, 0
	s_mov_b64 s[12:13], 0x10000
	s_mov_b64 s[14:15], 0x2000
	v_mov_b64_e32 v[4:5], v[2:3]
	s_mov_b32 s22, 0
	v_readlane_b32 s37, v253, 42
	v_readlane_b32 s38, v253, 43
	v_readlane_b32 s39, v253, 44
	v_readlane_b32 s40, v253, 45
	v_readlane_b32 s41, v253, 46
	v_readlane_b32 s42, v253, 47
	v_readlane_b32 s43, v253, 48
	v_readlane_b32 s44, v253, 49
	v_readlane_b32 s45, v253, 50
	v_readlane_b32 s46, v253, 51
	v_readlane_b32 s47, v253, 52
	s_cmp_lt_u32 s22, 3
	s_cbranch_scc1 .LBB0_316
.LBB0_305:
	global_load_dword v2, v3, s[4:5] sc1
	s_add_i32 s2, s22, -2
	s_waitcnt vmcnt(0)
	v_cmp_le_i32_e32 vcc, s2, v2
	s_cbranch_vccnz .LBB0_316
	s_movk_i32 s18, 0x1f8
	s_branch .LBB0_308

.LBB0_316:
	s_lshl_b32 s16, s22, 3
	v_lshl_add_u32 v2, s22, 16, v14
	s_add_i32 s2, s22, s20
	s_add_i32 s16, s16, s21
	s_mov_b32 s17, s3
	v_or_b32_e32 v2, v2, v1
	s_mov_b64 s[18:19], -1
	s_and_b64 vcc, exec, s[6:7]
	s_nop 0
	s_andn2_b64 vcc, exec, s[18:19]
	s_cbranch_vccz .LBB0_320

.LBB0_319:
	v_mov_b64_e32 v[10:11], v[6:7]
	s_lshl_b64 s[18:19], s[2:3], 14
	v_readlane_b32 s36, v253, 23
	v_lshl_add_u64 v[16:17], v[2:3], 1, s[10:11]
	v_mov_b64_e32 v[8:9], v[4:5]
	v_readlane_b32 s37, v253, 24
	s_add_u32 s34, s36, s18
	s_nop 0
	v_lshl_add_u64 v[16:17], v[16:17], 0, s[12:13]
	s_addc_u32 s35, s37, s19
	v_mov_b32_e32 v13, v3
	s_nop 0
	v_lshl_add_u64 v[16:17], s[34:35], 0, v[12:13]
	v_readlane_b32 s34, v253, 21
	v_readlane_b32 s35, v253, 22
	s_add_u32 s18, s34, s18
	s_nop 0
	v_lshl_add_u64 v[16:17], v[16:17], 0, s[14:15]
	s_addc_u32 s19, s35, s19
	s_nop 0
	v_lshl_add_u64 v[16:17], s[18:19], 0, v[12:13]
	s_lshl_b64 s[18:19], s[16:17], 13
	s_nop 0
	s_add_u32 s18, s8, s18
	v_lshl_add_u64 v[16:17], v[16:17], 0, s[14:15]
	s_nop 0
	s_addc_u32 s19, s9, s19
	v_readlane_b32 s38, v253, 25
	v_readlane_b32 s39, v253, 26
	v_lshl_add_u64 v[16:17], s[18:19], 0, v[12:13]
	s_nop 0
	s_cbranch_execnz .LBB0_318
.LBB0_320:
	v_lshlrev_b64 v[8:9], 1, v[2:3]
	s_lshl_b64 s[18:19], s[2:3], 14
	v_readlane_b32 s36, v253, 29
	v_lshl_add_u64 v[10:11], s[60:61], 0, v[8:9]
	s_mov_b64 exec, s[98:99]
	global_load_dwordx4 v[4:7], v[10:11], off
	s_mov_b64 exec, -1
	v_readlane_b32 s37, v253, 30
	v_readlane_b32 s38, v253, 31
	v_readlane_b32 s39, v253, 32
	s_add_u32 s34, s36, s18
	v_lshl_add_u64 v[10:11], v[10:11], 0, s[12:13]
	s_mov_b64 exec, s[98:99]
	global_load_dwordx4 v[4:7], v[10:11], off
	s_mov_b64 exec, -1
	v_lshl_add_u64 v[8:9], s[70:71], 0, v[8:9]
	s_addc_u32 s35, s37, s19
	v_readlane_b32 s36, v253, 41
	s_mov_b64 exec, s[98:99]
	global_load_dwordx4 v[4:7], v[8:9], off
	s_mov_b64 exec, -1
	v_lshl_add_u64 v[8:9], v[8:9], 0, s[12:13]
	v_mov_b32_e32 v13, v3
	v_readlane_b32 s48, v253, 53
	s_mov_b64 exec, s[98:99]
	global_load_dwordx4 v[4:7], v[8:9], off
	s_mov_b64 exec, -1
	v_lshl_add_u64 v[8:9], s[34:35], 0, v[12:13]
	v_readlane_b32 s49, v253, 54
	s_add_u32 s18, s48, s18
	s_mov_b64 exec, s[6:7]
	global_load_dwordx4 v[4:7], v[8:9], off
	s_mov_b64 exec, -1
	v_lshl_add_u64 v[8:9], v[8:9], 0, s[14:15]
	s_addc_u32 s19, s49, s19
	s_lshl_b64 s[16:17], s[16:17], 13
	s_mov_b64 exec, s[6:7]
	global_load_dwordx4 v[4:7], v[8:9], off
	s_mov_b64 exec, -1
	v_lshl_add_u64 v[8:9], s[18:19], 0, v[12:13]
	s_add_u32 s18, s0, s16
	s_addc_u32 s19, s1, s17
	s_mov_b64 exec, s[6:7]
	global_load_dwordx4 v[4:7], v[8:9], off
	s_mov_b64 exec, -1
	v_lshl_add_u64 v[8:9], v[8:9], 0, s[14:15]
	s_add_u32 s16, s88, s16
	v_readlane_b32 s2, v253, 33
	s_mov_b64 exec, s[6:7]
	global_load_dwordx4 v[4:7], v[8:9], off
	s_mov_b64 exec, -1
	v_lshl_add_u64 v[8:9], s[18:19], 0, v[12:13]
	s_addc_u32 s17, s2, s17
	s_mov_b64 exec, s[6:7]
	global_load_dwordx4 v[4:7], v[8:9], off
	s_mov_b64 exec, -1
	v_lshl_add_u64 v[8:9], s[16:17], 0, v[12:13]
	s_mov_b64 exec, s[6:7]
	global_load_dwordx4 v[4:7], v[8:9], off
	s_mov_b64 exec, -1
	v_readlane_b32 s37, v253, 42
	v_mov_b64_e32 v[10:11], v[6:7]
	v_mov_b64_e32 v[8:9], v[4:5]
	v_readlane_b32 s38, v253, 43
	v_readlane_b32 s39, v253, 44
	v_readlane_b32 s40, v253, 45
	v_readlane_b32 s41, v253, 46
	v_readlane_b32 s42, v253, 47
	v_readlane_b32 s43, v253, 48
	v_readlane_b32 s44, v253, 49
	v_readlane_b32 s45, v253, 50
	v_readlane_b32 s46, v253, 51
	v_readlane_b32 s47, v253, 52
	v_readlane_b32 s50, v253, 55
	v_readlane_b32 s51, v253, 56
	s_add_i32 s22, s22, 1
	s_cmp_eq_u32 s22, 64
	s_cbranch_scc1 .LBB0_322
.LBB0_321:
	v_mov_b64_e32 v[4:5], v[8:9]
	v_mov_b64_e32 v[6:7], v[10:11]
	s_cmp_lt_u32 s22, 3
	s_cbranch_scc0 .LBB0_305
	s_branch .LBB0_316

	.amdhsa_kernel _Z7hyb_fwd4Args
		.amdhsa_group_segment_fixed_size 0
		.amdhsa_private_segment_fixed_size 0
		.amdhsa_kernarg_size 400
		.amdhsa_user_sgpr_count 2
		.amdhsa_user_sgpr_dispatch_ptr 0
		.amdhsa_user_sgpr_queue_ptr 0
		.amdhsa_user_sgpr_kernarg_segment_ptr 1
		.amdhsa_user_sgpr_dispatch_id 0
		.amdhsa_user_sgpr_kernarg_preload_length 0
		.amdhsa_user_sgpr_kernarg_preload_offset 0
		.amdhsa_user_sgpr_private_segment_size 0
		.amdhsa_uses_dynamic_stack 0
		.amdhsa_enable_private_segment 0
		.amdhsa_system_sgpr_workgroup_id_x 1
		.amdhsa_system_sgpr_workgroup_id_y 0
		.amdhsa_system_sgpr_workgroup_id_z 0
		.amdhsa_system_sgpr_workgroup_info 0
		.amdhsa_system_vgpr_workitem_id 0
		.amdhsa_next_free_vgpr 254
		.amdhsa_next_free_sgpr 100
		.amdhsa_accum_offset 256
		.amdhsa_reserve_vcc 1
		.amdhsa_float_round_mode_32 0
		.amdhsa_float_round_mode_16_64 0
		.amdhsa_float_denorm_mode_32 3
		.amdhsa_float_denorm_mode_16_64 3
		.amdhsa_dx10_clamp 1
		.amdhsa_ieee_mode 1
		.amdhsa_fp16_overflow 0
		.amdhsa_tg_split 0
		.amdhsa_exception_fp_ieee_invalid_op 0
		.amdhsa_exception_fp_denorm_src 0
		.amdhsa_exception_fp_ieee_div_zero 0
		.amdhsa_exception_fp_ieee_overflow 0
		.amdhsa_exception_fp_ieee_underflow 0
		.amdhsa_exception_fp_ieee_inexact 0
		.amdhsa_exception_int_div_zero 0
	.end_amdhsa_kernel

amdhsa.kernels:
  - .agpr_count:     0
    .args:
      - .offset:         0
        .size:           144
        .value_kind:     by_value
      - .offset:         144
        .size:           4
        .value_kind:     hidden_block_count_x
      - .offset:         148
        .size:           4
        .value_kind:     hidden_block_count_y
      - .offset:         152
        .size:           4
        .value_kind:     hidden_block_count_z
      - .offset:         156
        .size:           2
        .value_kind:     hidden_group_size_x
      - .offset:         158
        .size:           2
        .value_kind:     hidden_group_size_y
      - .offset:         160
        .size:           2
        .value_kind:     hidden_group_size_z
      - .offset:         162
        .size:           2
        .value_kind:     hidden_remainder_x
      - .offset:         164
        .size:           2
        .value_kind:     hidden_remainder_y
      - .offset:         166
        .size:           2
        .value_kind:     hidden_remainder_z
      - .offset:         184
        .size:           8
        .value_kind:     hidden_global_offset_x
      - .offset:         192
        .size:           8
        .value_kind:     hidden_global_offset_y
      - .offset:         200
        .size:           8
        .value_kind:     hidden_global_offset_z
      - .offset:         208
        .size:           2
        .value_kind:     hidden_grid_dims
      - .offset:         264
        .size:           4
        .value_kind:     hidden_dynamic_lds_size
    .group_segment_fixed_size: 0
    .kernarg_segment_align: 8
    .kernarg_segment_size: 400
    .language:       OpenCL C
    .language_version:
      - 2
      - 0
    .max_flat_workgroup_size: 512
    .name:           _Z7hyb_fwd4Args
    .private_segment_fixed_size: 0
    .sgpr_count:     106
    .sgpr_spill_count: 68
    .symbol:         _Z7hyb_fwd4Args.kd
    .uniform_work_group_size: 1
    .uses_dynamic_stack: false
    .vgpr_count:     254
    .vgpr_spill_count: 0
    .wavefront_size: 64
